# row-wise N2 loop only: fresh-register ring copies moved to the iteration end behind one counted vmcnt
# baseline (speedup 1.0000x reference)
; __device__ __forceinline__ int tidx() { int t = threadIdx.x & 255; asm volatile("" : "+v"(t)); return t; }
; __device__ __forceinline__ void rowwise_phase(CP p, int mode, const float* wpost, const float* wpre, bool write_hn, int nparts) {
;   const int tid_ = tidx(); const int lane = tid_ & 63, gw = bidx() * 4 + (tid_ >> 6), nw = nvb() * 4;
;   const float* tmp = (const float*)(p.ws + WS_TMP);
;   bf16_t* hn = (bf16_t*)(p.ws + WS_Y);
;   float4 wpo[4], wpr[4];
; #pragma unroll
;   for (int q = 0; q < 4; ++q) {
;     wpo[q] = (mode != 0) ? *reinterpret_cast<const float4*>(wpost + q * 256 + lane * 4) : make_float4(0.f, 0.f, 0.f, 0.f);
;     wpr[q] = write_hn ? *reinterpret_cast<const float4*>(wpre + q * 256 + lane * 4) : make_float4(0.f, 0.f, 0.f, 0.f);
;   }
;   float4 tv[4], hv[4], tvn[4], hvn[4], tvm[4], hvm[4];
;   auto loadrow = [&](int row, float4 (&t)[4], float4 (&h)[4]) {
;     if (mode == 0) {
;       const float* src = row < RREAL ? p.in[0] + (size_t)row * D : p.in[1] + (size_t)((row - RREAL) & 15) * D;
; #pragma unroll
;       for (int q = 0; q < 4; ++q) { h[q] = *reinterpret_cast<const float4*>(src + q * 256 + lane * 4); t[q] = make_float4(0.f, 0.f, 0.f, 0.f); }
;     } else {
;       const float* hr = hrow_ptr(p, row);
; #pragma unroll
;       for (int q = 0; q < 4; ++q) {
;         if (row < RREAL) {
;           {
;             const float* tp_ = tmp + (size_t)row * D + q * 256 + lane * 4;
;             t[q] = make_float4(__builtin_nontemporal_load(tp_), __builtin_nontemporal_load(tp_ + 1), __builtin_nontemporal_load(tp_ + 2), __builtin_nontemporal_load(tp_ + 3));
;           }
;         } else {
;           const float* pp = (const float*)(p.ws + WS_PART) + (size_t)(row - RREAL) * D + q * 256 + lane * 4;
;           float4 a = *reinterpret_cast<const float4*>(pp);
;           for (int kc = 1; kc < nparts; ++kc) {
;             const float4 c = *reinterpret_cast<const float4*>(pp + (size_t)kc * 128 * 1024);
;             a.x += c.x; a.y += c.y; a.z += c.z; a.w += c.w;
;           }
;           t[q] = a;
;         }
;         h[q] = *reinterpret_cast<const float4*>(hr + q * 256 + lane * 4);
;       }
;     }
;   };
;   if (gw < R) loadrow(gw, tv, hv);
;   if (gw + nw < R) loadrow(gw + nw, tvn, hvn);
;   for (int row = gw; row < R; row += nw) {
.LBB0_280:
	s_movk_i32 s0, 0x407f
	s_or_b64 exec, exec, s[44:45]
	s_and_saveexec_b64 s[42:43], s[38:39]
	s_cbranch_execz .LBB0_301
	v_readlane_b32 s2, v253, 63
	v_readlane_b32 s3, v254, 0
	s_load_dwordx2 s[44:45], s[2:3], 0x120
	v_lshl_add_u64 v[98:99], s[92:93], 0, v[148:149]
	s_mov_b64 s[2:3], 0xded0800
	v_and_b32_e32 v97, 64, v217
	v_lshl_add_u64 v[130:131], v[98:99], 0, s[2:3]
	v_add_u32_e32 v97, 64, v97
	v_xor_b32_e32 v98, 32, v217
	v_cmp_lt_i32_e32 vcc, v98, v97
	v_readlane_b32 s2, v254, 1
	v_and_b32_e32 v96, 63, v96
	v_cndmask_b32_e32 v98, v217, v98, vcc
	v_lshlrev_b32_e32 v138, 2, v98
	v_xor_b32_e32 v98, 16, v217
	v_cmp_lt_i32_e32 vcc, v98, v97
	v_readlane_b32 s3, v254, 2
	s_add_u32 s10, s92, 0x4000
	v_cndmask_b32_e32 v98, v217, v98, vcc
	v_lshlrev_b32_e32 v139, 2, v98
	v_xor_b32_e32 v98, 8, v217
	v_cmp_lt_i32_e32 vcc, v98, v97
	v_lshl_add_u64 v[132:133], s[2:3], 0, v[148:149]
	s_mov_b64 s[2:3], 0x7a90e04
	v_cndmask_b32_e32 v98, v217, v98, vcc
	v_lshlrev_b32_e32 v140, 2, v98
	v_xor_b32_e32 v98, 4, v217
	v_cmp_lt_i32_e32 vcc, v98, v97
	s_addc_u32 s11, s93, 0
	s_mov_b64 s[72:73], 0
	v_cndmask_b32_e32 v98, v217, v98, vcc
	v_lshlrev_b32_e32 v141, 2, v98
	v_xor_b32_e32 v98, 2, v217
	v_cmp_lt_i32_e32 vcc, v98, v97
	s_mov_b64 s[74:75], 0
	v_mov_b32_e32 v144, v128
	v_cndmask_b32_e32 v98, v217, v98, vcc
	v_lshlrev_b32_e32 v142, 2, v98
	v_xor_b32_e32 v98, 1, v217
	v_cmp_lt_i32_e32 vcc, v98, v97
	s_nop 1
	v_cndmask_b32_e32 v97, v217, v98, vcc
	v_lshlrev_b64 v[98:99], 11, v[128:129]
	v_lshl_or_b32 v98, v96, 3, v98
	v_lshlrev_b32_e32 v143, 2, v97
	v_lshl_add_u64 v[96:97], s[92:93], 0, v[98:99]
	v_lshl_add_u64 v[134:135], v[96:97], 0, s[2:3]
	s_waitcnt vmcnt(0)
	s_branch .LBB0_284

; __device__ __forceinline__ void rowwise_phase(CP p, int mode, const float* wpost, const float* wpre, bool write_hn, int nparts) {
;     ...
;     if (mode != 0) {
;       float ss = 0.f;
; #pragma unroll
;       for (int q = 0; q < 4; ++q) ss += tv[q].x * tv[q].x + tv[q].y * tv[q].y + tv[q].z * tv[q].z + tv[q].w * tv[q].w;
;       ss = wave_sum(ss);
;       const float rs = rsqrtf(ss * (1.f / D) + EPS);
; #pragma unroll
;       for (int q = 0; q < 4; ++q) {
;         hv[q].x += tv[q].x * rs * wpo[q].x;
;         hv[q].y += tv[q].y * rs * wpo[q].y;
;         hv[q].z += tv[q].z * rs * wpo[q].z;
;         hv[q].w += tv[q].w * rs * wpo[q].w;
;       }
;     }
; #pragma unroll
;     for (int q = 0; q < 4; ++q) {
;       float* hp_ = hr + q * 256 + lane * 4;
;       __builtin_nontemporal_store(hv[q].x, hp_); __builtin_nontemporal_store(hv[q].y, hp_ + 1);
;       __builtin_nontemporal_store(hv[q].z, hp_ + 2); __builtin_nontemporal_store(hv[q].w, hp_ + 3);
;     }
;     if (write_hn) {
;       float ss = 0.f;
; #pragma unroll
;       for (int q = 0; q < 4; ++q) ss += hv[q].x * hv[q].x + hv[q].y * hv[q].y + hv[q].z * hv[q].z + hv[q].w * hv[q].w;
;       ss = wave_sum(ss);
;       const float rs = rsqrtf(ss * (1.f / D) + EPS);
.LBB0_283:
	s_or_b64 exec, exec, s[2:3]
	v_mov_b32_e32 v136, v40
	v_mov_b32_e32 v137, v32
	v_pk_mul_f32 v[136:137], v[136:137], v[136:137]
	v_mov_b32_e32 v146, v41
	v_mov_b32_e32 v147, v33
	v_pk_fma_f32 v[136:137], v[146:147], v[146:147], v[136:137]
	v_mov_b32_e32 v146, v42
	v_mov_b32_e32 v147, v34
	v_pk_fma_f32 v[136:137], v[146:147], v[146:147], v[136:137]
	v_mov_b32_e32 v146, v43
	v_mov_b32_e32 v147, v35
	v_pk_fma_f32 v[136:137], v[146:147], v[146:147], v[136:137]
	v_mov_b32_e32 v146, v56
	v_mov_b32_e32 v147, v48
	v_pk_mul_f32 v[146:147], v[146:147], v[146:147]
	v_mov_b32_e32 v152, v57
	v_mov_b32_e32 v153, v49
	v_pk_fma_f32 v[146:147], v[152:153], v[152:153], v[146:147]
	v_mov_b32_e32 v152, v58
	v_mov_b32_e32 v153, v50
	v_pk_fma_f32 v[146:147], v[152:153], v[152:153], v[146:147]
	v_mov_b32_e32 v152, v59
	v_mov_b32_e32 v153, v51
	v_pk_fma_f32 v[146:147], v[152:153], v[152:153], v[146:147]
	v_add_f32_e32 v136, v136, v137
	v_add_f32_e32 v136, v147, v136
	v_add_f32_e32 v136, v146, v136
	ds_bpermute_b32 v137, v138, v136
	v_readlane_b32 s2, v253, 49
	v_readlane_b32 s3, v253, 50
	s_waitcnt lgkmcnt(0)
	v_add_f32_e32 v136, v136, v137
	ds_bpermute_b32 v137, v139, v136
	s_waitcnt lgkmcnt(0)
	v_add_f32_e32 v136, v136, v137
	ds_bpermute_b32 v137, v140, v136
	s_waitcnt lgkmcnt(0)
	v_add_f32_e32 v136, v136, v137
	ds_bpermute_b32 v137, v141, v136
	s_waitcnt lgkmcnt(0)
	v_add_f32_e32 v136, v136, v137
	ds_bpermute_b32 v137, v142, v136
	s_waitcnt lgkmcnt(0)
	v_add_f32_e32 v136, v136, v137
	ds_bpermute_b32 v137, v143, v136
	s_waitcnt lgkmcnt(0)
	v_add_f32_e32 v136, v136, v137
	v_fmamk_f32 v136, v136, 0x3a800000, v215
	v_mul_f32_e32 v137, 0x4b800000, v136
	v_cmp_gt_f32_e32 vcc, s33, v136
	s_nop 1
	v_cndmask_b32_e32 v136, v136, v137, vcc
	v_rsq_f32_e32 v136, v136
	s_nop 0
	v_mul_f32_e32 v137, 0x45800000, v136
	v_cndmask_b32_e32 v136, v136, v137, vcc
	v_pk_mul_f32 v[32:33], v[32:33], v[136:137] op_sel_hi:[1,0]
	v_pk_mul_f32 v[40:41], v[40:41], v[136:137] op_sel_hi:[1,0]
	v_pk_mul_f32 v[34:35], v[34:35], v[136:137] op_sel_hi:[1,0]
	v_pk_mul_f32 v[42:43], v[42:43], v[136:137] op_sel_hi:[1,0]
	v_pk_fma_f32 v[32:33], v[0:1], v[32:33], v[36:37]
	v_pk_fma_f32 v[36:37], v[4:5], v[40:41], v[44:45]
	v_pk_mul_f32 v[48:49], v[48:49], v[136:137] op_sel_hi:[1,0]
	v_pk_fma_f32 v[34:35], v[2:3], v[34:35], v[38:39]
	v_pk_fma_f32 v[38:39], v[6:7], v[42:43], v[46:47]
	v_pk_mul_f32 v[42:43], v[50:51], v[136:137] op_sel_hi:[1,0]
	v_mov_b32_e32 v50, v33
	v_mov_b32_e32 v51, v37
	v_pk_fma_f32 v[40:41], v[16:17], v[48:49], v[52:53]
	v_pk_mul_f32 v[44:45], v[56:57], v[136:137] op_sel_hi:[1,0]
	v_mov_b32_e32 v48, v32
	v_mov_b32_e32 v49, v36
	v_pk_mul_f32 v[50:51], v[50:51], v[50:51]
	v_pk_fma_f32 v[44:45], v[20:21], v[44:45], v[64:65]
	v_pk_fma_f32 v[48:49], v[48:49], v[48:49], v[50:51]
	v_mov_b32_e32 v50, v34
	v_mov_b32_e32 v51, v38
	v_pk_mul_f32 v[46:47], v[58:59], v[136:137] op_sel_hi:[1,0]
	v_pk_fma_f32 v[48:49], v[50:51], v[50:51], v[48:49]
	v_mov_b32_e32 v50, v35
	v_mov_b32_e32 v51, v39
	v_mov_b32_e32 v52, v45
	v_mov_b32_e32 v53, v41
	v_pk_fma_f32 v[42:43], v[18:19], v[42:43], v[54:55]
	v_pk_fma_f32 v[46:47], v[22:23], v[46:47], v[66:67]
	v_pk_fma_f32 v[48:49], v[50:51], v[50:51], v[48:49]
	v_mov_b32_e32 v50, v44
	v_mov_b32_e32 v51, v40
	v_pk_mul_f32 v[52:53], v[52:53], v[52:53]
	v_add_f32_e32 v48, v48, v49
	v_pk_fma_f32 v[50:51], v[50:51], v[50:51], v[52:53]
	v_mov_b32_e32 v52, v46
	v_mov_b32_e32 v53, v42
	v_pk_fma_f32 v[50:51], v[52:53], v[52:53], v[50:51]
	v_mov_b32_e32 v52, v47
	v_mov_b32_e32 v53, v43
	v_pk_fma_f32 v[50:51], v[52:53], v[52:53], v[50:51]
	v_add_u32_e32 v52, 0xffffc000, v144
	v_add_f32_e32 v48, v51, v48
	v_add_f32_e32 v48, v50, v48
	ds_bpermute_b32 v49, v138, v48
	v_cmp_gt_i32_e32 vcc, s55, v144
	v_mov_b32_e32 v53, s45
	v_add_u32_e32 v144, s60, v144
	v_mov_b64_e32 v[64:65], v[92:93]
	s_waitcnt lgkmcnt(0)
; __device__ __forceinline__ void rowwise_phase(CP p, int mode, const float* wpost, const float* wpre, bool write_hn, int nparts) {
;     ...
; #pragma unroll
;     for (int q = 0; q < 4; ++q) {
;       float* hp_ = hr + q * 256 + lane * 4;
;       __builtin_nontemporal_store(hv[q].x, hp_); __builtin_nontemporal_store(hv[q].y, hp_ + 1);
;       __builtin_nontemporal_store(hv[q].z, hp_ + 2); __builtin_nontemporal_store(hv[q].w, hp_ + 3);
;     }
;     if (write_hn) {
;       float ss = 0.f;
; #pragma unroll
;       for (int q = 0; q < 4; ++q) ss += hv[q].x * hv[q].x + hv[q].y * hv[q].y + hv[q].z * hv[q].z + hv[q].w * hv[q].w;
;       ss = wave_sum(ss);
;       const float rs = rsqrtf(ss * (1.f / D) + EPS);
; #pragma unroll
;       for (int q = 0; q < 4; ++q) {
;         uint2 o;
;         o.x = pack2(hv[q].x * rs * wpr[q].x, hv[q].y * rs * wpr[q].y);
;         o.y = pack2(hv[q].z * rs * wpr[q].z, hv[q].w * rs * wpr[q].w);
;         *reinterpret_cast<uint2*>(hn + (size_t)row * D + q * 256 + lane * 4) = o;
;       }
;     }
; #pragma unroll
;     for (int q = 0; q < 4; ++q) { tv[q] = tvn[q]; hv[q] = hvn[q]; tvn[q] = tvm[q]; hvn[q] = hvm[q]; }
	v_add_f32_e32 v48, v48, v49
	ds_bpermute_b32 v49, v139, v48
	v_mov_b64_e32 v[56:57], v[88:89]
	v_mov_b64_e32 v[66:67], v[94:95]
	s_waitcnt lgkmcnt(0)
	v_add_f32_e32 v50, v48, v49
	ds_bpermute_b32 v51, v140, v50
	v_lshl_add_u64 v[48:49], v[128:129], 0, s[74:75]
	v_cndmask_b32_e32 v48, v52, v48, vcc
	v_mov_b32_e32 v52, s11
	v_cndmask_b32_e32 v49, 0, v49, vcc
	s_waitcnt lgkmcnt(0)
	v_add_f32_e32 v50, v50, v51
	ds_bpermute_b32 v51, v141, v50
	v_lshlrev_b64 v[48:49], 12, v[48:49]
	s_add_u32 s74, s74, s60
	s_addc_u32 s75, s75, s61
	s_waitcnt lgkmcnt(0)
	v_add_f32_e32 v54, v50, v51
	ds_bpermute_b32 v55, v142, v54
	v_cndmask_b32_e32 v51, v52, v53, vcc
	v_mov_b32_e32 v50, s10
	v_mov_b32_e32 v52, s44
	v_cndmask_b32_e32 v50, v50, v52, vcc
	s_waitcnt lgkmcnt(0)
	v_add_f32_e32 v52, v54, v55
	ds_bpermute_b32 v53, v143, v52
	v_lshl_add_u64 v[48:49], v[50:51], 0, v[48:49]
	v_lshl_add_u64 v[48:49], v[48:49], 0, v[148:149]
	global_store_dwordx4 v[48:49], v[32:35], off nt
	global_store_dwordx4 v[48:49], v[36:39], off offset:1024 nt
	global_store_dwordx4 v[48:49], v[40:43], off offset:2048 nt
	global_store_dwordx4 v[48:49], v[44:47], off offset:3072 nt
	s_waitcnt lgkmcnt(0)
	v_add_f32_e32 v50, v52, v53
	v_fmamk_f32 v50, v50, 0x3a800000, v215
	v_mul_f32_e32 v51, 0x4b800000, v50
	v_cmp_gt_f32_e32 vcc, s33, v50
	v_mov_b64_e32 v[52:53], v[84:85]
	v_cndmask_b32_e32 v50, v50, v51, vcc
	v_rsq_f32_e32 v50, v50
	v_mov_b64_e32 v[54:55], v[86:87]
	v_mov_b64_e32 v[58:59], v[90:91]
	v_mul_f32_e32 v48, 0x45800000, v50
	v_cndmask_b32_e32 v48, v50, v48, vcc
	v_pk_mul_f32 v[32:33], v[32:33], v[48:49] op_sel_hi:[1,0]
	v_pk_mul_f32 v[34:35], v[34:35], v[48:49] op_sel_hi:[1,0]
	v_pk_mul_f32 v[32:33], v[8:9], v[32:33]
	v_pk_mul_f32 v[34:35], v[10:11], v[34:35]
	v_cvt_pk_bf16_f32 v32, v32, v33
	v_cvt_pk_bf16_f32 v33, v34, v35
	global_store_dwordx2 v[134:135], v[32:33], off offset:-1540
	v_pk_mul_f32 v[32:33], v[36:37], v[48:49] op_sel_hi:[1,0]
	v_pk_mul_f32 v[34:35], v[38:39], v[48:49] op_sel_hi:[1,0]
	v_pk_mul_f32 v[32:33], v[12:13], v[32:33]
	v_pk_mul_f32 v[34:35], v[14:15], v[34:35]
	v_cvt_pk_bf16_f32 v32, v32, v33
	v_cvt_pk_bf16_f32 v33, v34, v35
	global_store_dwordx2 v[134:135], v[32:33], off offset:-1028
	v_pk_mul_f32 v[32:33], v[40:41], v[48:49] op_sel_hi:[1,0]
	v_pk_mul_f32 v[34:35], v[42:43], v[48:49] op_sel_hi:[1,0]
	v_pk_mul_f32 v[32:33], v[24:25], v[32:33]
	v_pk_mul_f32 v[34:35], v[26:27], v[34:35]
	v_cvt_pk_bf16_f32 v32, v32, v33
	v_cvt_pk_bf16_f32 v33, v34, v35
	global_store_dwordx2 v[134:135], v[32:33], off offset:-516
	v_pk_mul_f32 v[32:33], v[44:45], v[48:49] op_sel_hi:[1,0]
	v_pk_mul_f32 v[34:35], v[46:47], v[48:49] op_sel_hi:[1,0]
	v_pk_mul_f32 v[32:33], v[28:29], v[32:33]
	v_pk_mul_f32 v[34:35], v[30:31], v[34:35]
	v_cvt_pk_bf16_f32 v32, v32, v33
	v_cvt_pk_bf16_f32 v33, v34, v35
	v_cmp_lt_i32_e32 vcc, s0, v144
	global_store_dwordx2 v[134:135], v[32:33], off offset:-4
	v_lshl_add_u64 v[134:135], v[134:135], 0, s[2:3]
	s_or_b64 s[72:73], vcc, s[72:73]
	v_mov_b64_e32 v[36:37], v[68:69]
	v_mov_b64_e32 v[32:33], v[60:61]
	v_mov_b64_e32 v[38:39], v[70:71]
	v_mov_b64_e32 v[34:35], v[62:63]
	v_mov_b64_e32 v[44:45], v[76:77]
	v_mov_b64_e32 v[40:41], v[72:73]
	v_mov_b64_e32 v[46:47], v[78:79]
	v_mov_b64_e32 v[42:43], v[74:75]
	v_mov_b64_e32 v[48:49], v[80:81]
	v_mov_b64_e32 v[50:51], v[82:83]
	s_waitcnt vmcnt(8)
	v_mov_b64_e32 v[92:93], v[124:125]
	v_mov_b64_e32 v[88:89], v[120:121]
	v_mov_b64_e32 v[94:95], v[126:127]
	v_mov_b64_e32 v[84:85], v[116:117]
	v_mov_b64_e32 v[86:87], v[118:119]
	v_mov_b64_e32 v[68:69], v[100:101]
	v_mov_b64_e32 v[60:61], v[96:97]
	v_mov_b64_e32 v[70:71], v[102:103]
	v_mov_b64_e32 v[62:63], v[98:99]
	v_mov_b64_e32 v[76:77], v[108:109]
	v_mov_b64_e32 v[72:73], v[104:105]
	v_mov_b64_e32 v[78:79], v[110:111]
	v_mov_b64_e32 v[74:75], v[106:107]
	v_mov_b64_e32 v[80:81], v[112:113]
	v_mov_b64_e32 v[82:83], v[114:115]
	v_mov_b64_e32 v[90:91], v[122:123]
	s_andn2_b64 exec, exec, s[72:73]
	s_cbranch_execz .LBB0_301
